# k27: k26 + the moved scan prefetch block split into 4 chunks interleaved with the first four QK MFMA steps (fills LDS-wait stalls)
# baseline (speedup 1.0000x reference)
; __device__ __forceinline__ void ret_item(LAS unsigned char* lds, const bf16_t* proj, bf16_t* OD, int b, int h, int dir, int vs, float lg2) {
;     ...
;         if (step + 1 < 64) { const int c1 = dir ? 62 - step : step + 1; const size_t t1 = (size_t)c1 * CH;
; #pragma unroll
;             for (int k = 0; k < 4; ++k) { pq[k] = *(const bf16x8*)(Qg + (t1 + qrow + 16 * k) * R_IN + qpc * 8); pk[k] = *(const bf16x8*)(Kg + (t1 + qrow + 16 * k) * R_IN + qpc * 8); }
; #pragma unroll
;             for (int k = 0; k < 2; ++k) pv[k] = *(const bf16x8*)(Vg + (t1 + vrow + 32 * k) * R_IN + vpc * 8);
;         }
;         RBAR();
;         {   f32x4 sa0 = (f32x4){0.f, 0.f, 0.f, 0.f}, sa1 = sa0;
;             s16x4 fq[2][2]; bf16x8 fk0[2], fk1[2];
;     ...
;             LDS_S(0, 0);
; #pragma unroll
;             for (int s = 0; s < 8; ++s) { if (s < 7) LDS_S((s + 1) & 1, s + 1); SCHED();
;                 const bf16x8 bq = cat(fq[s & 1][0], fq[s & 1][1]);
;                 __builtin_amdgcn_s_setprio(1); sa0 = MF16(fk0[s & 1], bq, sa0); sa1 = MF16(fk1[s & 1], bq, sa1); __builtin_amdgcn_s_setprio(0); SCHED(); }
;     ...
; #pragma unroll
;             for (int tt = 0; tt < 2; ++tt) { const f32x4 sv = tt ? sa1 : sa0; const int dt = dir ? (sjt0 + tt - sit) : (sit - sjt0 - tt);
;                 const float cs = dt <= 0 ? 1.f : dt == 1 ? c16 : dt == 2 ? c32 : c48; float w[4];
; #pragma unroll
;                 for (int r = 0; r < 4; ++r) { const bool on = dt > 0 || (dt == 0 && (dir ? (4 * g + r > l15) : (l15 >= 4 * g + r))); w[r] = on ? sv[r] * d4[r] * cs : 0.f; }
;                 u32x2 pkd; pkd.x = cvtpk(w[0], w[1]); pkd.y = cvtpk(w[2], w[3]);
;                 *(LAS u32x2*)(lds + SP + (16 * sit + l15) * RSS + (16 * (sjt0 + tt) + 4 * g) * 2) = pkd; }
;     ...
;         {   bf16x8 ca[2][4];
;     ...
;             LDS_C(0, 0);
; #pragma unroll
;             for (int s = 0; s < 8; ++s) { if (s < 7) LDS_C((s + 1) & 1, s + 1); SCHED();
;                 u32x4 bw; bw.x = cvtpk(st[2 * s][0], st[2 * s][1]); bw.y = cvtpk(st[2 * s][2], st[2 * s][3]); bw.z = cvtpk(st[2 * s + 1][0], st[2 * s + 1][1]); bw.w = cvtpk(st[2 * s + 1][2], st[2 * s + 1][3]);
;                 const bf16x8 bs = __builtin_bit_cast(bf16x8, bw);
;                 __builtin_amdgcn_s_setprio(1);
; #pragma unroll
;                 for (int it = 0; it < 4; ++it) acc[it] = MF16(bs, ca[s & 1][it], acc[it]);
;                 __builtin_amdgcn_s_setprio(0); SCHED(); }
.Lscan_pf_skip0:
	s_setprio 1
	s_waitcnt lgkmcnt(4)
	v_mfma_f32_16x16x32_bf16 v[108:111], v[108:111], v[104:107], 0
	s_waitcnt lgkmcnt(3)
	v_mfma_f32_16x16x32_bf16 v[104:107], v[112:115], v[104:107], 0
	s_setprio 0
	ds_read2_b64 v[112:115], v229 offset0:16 offset1:18
	ds_read_b128 v[128:131], v230 offset:36992
	ds_read_b128 v[132:135], v230 offset:46208
	s_cmp_eq_u32 s19, -1
	s_cbranch_scc1 .Lscan_pf_skip1
	v_add_co_u32_e32 v12, vcc, s65, v26
	global_load_dwordx4 v[0:3], v[24:25], off
	global_load_dwordx4 v[4:7], v[26:27], off
	v_addc_co_u32_e32 v13, vcc, 0, v27, vcc
	v_add_co_u32_e32 v16, vcc, s64, v24
	v_lshl_add_u64 v[32:33], s[20:21], 0, v[166:167]
	s_nop 0
	v_addc_co_u32_e32 v17, vcc, 0, v25, vcc
	v_add_co_u32_e32 v20, vcc, s64, v26
	v_mad_u64_u32 v[34:35], s[20:21], v32, s3, v[172:173]
	s_nop 0
	v_addc_co_u32_e32 v21, vcc, 0, v27, vcc
.Lscan_pf_skip1:
	s_setprio 1
	s_waitcnt lgkmcnt(4)
	v_mfma_f32_16x16x32_bf16 v[108:111], v[120:123], v[116:119], v[108:111]
	s_waitcnt lgkmcnt(3)
	v_mfma_f32_16x16x32_bf16 v[104:107], v[124:127], v[116:119], v[104:107]
	s_setprio 0
	ds_read2_b64 v[116:119], v229 offset0:24 offset1:26
	ds_read_b128 v[120:123], v230 offset:37056
	ds_read_b128 v[124:127], v230 offset:46272
	s_cmp_eq_u32 s19, -1
	s_cbranch_scc1 .Lscan_pf_skip2
	v_add_co_u32_e32 v24, vcc, s70, v24
	v_mad_i32_i24 v35, v33, s3, v35
	s_nop 0
	v_addc_co_u32_e32 v25, vcc, 0, v25, vcc
	v_add_co_u32_e32 v28, vcc, 0x120000, v26
	global_load_dwordx4 v[8:11], v[8:9], off
	s_nop 0
	global_load_dwordx4 v[12:15], v[12:13], off
	v_addc_co_u32_e32 v29, vcc, 0, v27, vcc
	v_add_co_u32_e32 v36, vcc, 0xc0000, v34
.Lscan_pf_skip2:
	s_setprio 1
	s_waitcnt lgkmcnt(4)
	v_mfma_f32_16x16x32_bf16 v[108:111], v[128:131], v[112:115], v[108:111]
	s_waitcnt lgkmcnt(3)
	v_mfma_f32_16x16x32_bf16 v[104:107], v[132:135], v[112:115], v[104:107]
	s_setprio 0
	ds_read2_b64 v[112:115], v229 offset0:32 offset1:34
	ds_read_b128 v[128:131], v230 offset:37120
	ds_read_b128 v[132:135], v230 offset:46336
	s_cmp_eq_u32 s19, -1
	s_cbranch_scc1 .Lscan_pf_skip3
	global_load_dwordx4 v[16:19], v[16:17], off
	s_nop 0
	global_load_dwordx4 v[20:23], v[20:21], off
	v_addc_co_u32_e32 v37, vcc, 0, v35, vcc
	global_load_dwordx4 v[24:27], v[24:25], off
	s_nop 0
	global_load_dwordx4 v[28:31], v[28:29], off
	s_nop 0
	global_load_dwordx4 v[32:35], v[34:35], off
	s_nop 0
	global_load_dwordx4 v[36:39], v[36:37], off
.Lscan_pf_skip3:
	s_setprio 1
	s_waitcnt lgkmcnt(4)
	v_mfma_f32_16x16x32_bf16 v[108:111], v[120:123], v[116:119], v[108:111]
	s_waitcnt lgkmcnt(3)
	v_mfma_f32_16x16x32_bf16 v[104:107], v[124:127], v[116:119], v[104:107]
	s_setprio 0
	ds_read2_b64 v[116:119], v229 offset0:40 offset1:42
	ds_read_b128 v[120:123], v230 offset:37184
	ds_read_b128 v[124:127], v230 offset:46400
	s_setprio 1
	s_waitcnt lgkmcnt(4)
	v_mfma_f32_16x16x32_bf16 v[108:111], v[128:131], v[112:115], v[108:111]
	s_waitcnt lgkmcnt(3)
	v_mfma_f32_16x16x32_bf16 v[104:107], v[132:135], v[112:115], v[104:107]
	s_setprio 0
	ds_read2_b64 v[112:115], v229 offset0:48 offset1:50
	ds_read_b128 v[128:131], v230 offset:37248
	ds_read_b128 v[132:135], v230 offset:46464
	s_setprio 1
	s_waitcnt lgkmcnt(4)
	v_mfma_f32_16x16x32_bf16 v[108:111], v[120:123], v[116:119], v[108:111]
	s_waitcnt lgkmcnt(3)
	v_mfma_f32_16x16x32_bf16 v[104:107], v[124:127], v[116:119], v[104:107]
	s_setprio 0
	ds_read2_b64 v[116:119], v229 offset0:56 offset1:58
	ds_read_b128 v[120:123], v230 offset:37312
	ds_read_b128 v[124:127], v230 offset:46528
	s_setprio 1
	s_waitcnt lgkmcnt(4)
	v_mfma_f32_16x16x32_bf16 v[108:111], v[128:131], v[112:115], v[108:111]
	s_waitcnt lgkmcnt(3)
	v_mfma_f32_16x16x32_bf16 v[104:107], v[132:135], v[112:115], v[104:107]
	s_setprio 0
	s_setprio 1
	s_waitcnt lgkmcnt(1)
	v_mfma_f32_16x16x32_bf16 v[108:111], v[120:123], v[116:119], v[108:111]
	s_waitcnt lgkmcnt(0)
	v_mfma_f32_16x16x32_bf16 v[104:107], v[124:127], v[116:119], v[104:107]
	s_setprio 0
	s_nop 4
	v_mul_f32_e32 v108, v199, v108
	v_mul_f32_e32 v109, v200, v109
	v_mul_f32_e32 v110, v201, v110
	v_mul_f32_e32 v108, v206, v108
	v_mul_f32_e32 v109, v206, v109
	v_mul_f32_e32 v110, v206, v110
	v_mul_f32_e32 v111, v202, v111
	v_mul_f32_e32 v104, v199, v104
	v_mul_f32_e32 v105, v200, v105
	v_mul_f32_e32 v106, v201, v106
	v_cndmask_b32_e64 v108, 0, v108, s[38:39]
	v_cndmask_b32_e64 v109, 0, v109, s[40:41]
	v_cndmask_b32_e64 v110, 0, v110, s[42:43]
	v_mul_f32_e32 v111, v206, v111
	v_mul_f32_e32 v104, v207, v104
	v_mul_f32_e32 v105, v207, v105
	v_mul_f32_e32 v106, v207, v106
	v_mul_f32_e32 v107, v202, v107
	v_cndmask_b32_e64 v111, 0, v111, s[44:45]
	v_cvt_pk_bf16_f32 v108, v108, v109
	v_cvt_pk_bf16_f32 v109, v110, v111
	v_add_u32_e32 v110, s17, v205
	v_cndmask_b32_e64 v104, 0, v104, s[46:47]
	v_cndmask_b32_e64 v105, 0, v105, s[48:49]
	v_cndmask_b32_e64 v106, 0, v106, s[50:51]
	v_mul_f32_e32 v107, v207, v107
	ds_write_b64 v110, v[108:109]
	v_cndmask_b32_e64 v107, 0, v107, s[52:53]
	v_cvt_pk_bf16_f32 v104, v104, v105
	v_cvt_pk_bf16_f32 v105, v106, v107
	v_add_u32_e32 v106, s18, v205
	ds_write_b64 v106, v[104:105]
	ds_read_b128 v[104:107], v231
	ds_read_b128 v[108:111], v231 offset:64
	ds_read_b128 v[112:115], v231 offset:9216
	ds_read_b128 v[116:119], v231 offset:9280
	ds_read_b128 v[120:123], v231 offset:18432
	ds_read_b128 v[124:127], v231 offset:18496
	ds_read_b128 v[128:131], v231 offset:27648
	ds_read_b128 v[132:135], v231 offset:27712
	v_cvt_pk_bf16_f32 v136, v40, v41
	v_cvt_pk_bf16_f32 v137, v42, v43
	v_cvt_pk_bf16_f32 v138, v52, v53
	v_cvt_pk_bf16_f32 v139, v54, v55
	s_setprio 1
	s_waitcnt lgkmcnt(7)
	v_mfma_f32_16x16x32_bf16 v[104:107], v[136:139], v[104:107], 0
	s_waitcnt lgkmcnt(5)
; __device__ __forceinline__ unsigned cvtpk(float lo, float hi) { unsigned r; asm volatile("v_cvt_pk_bf16_f32 %0, %1, %2" : "=v"(r) : "v"(lo), "v"(hi)); return r; }
; #define MF16(a, b, c) __builtin_amdgcn_mfma_f32_16x16x32_bf16((a), (b), (c), 0, 0, 0)
; __device__ __forceinline__ unsigned cvtpk(float lo, float hi) { unsigned r; asm volatile("v_cvt_pk_bf16_f32 %0, %1, %2" : "=v"(r) : "v"(lo), "v"(hi)); return r; }
; #define SCHED() __builtin_amdgcn_sched_barrier(0)
; #define LDS_C(buf, s) do { _Pragma("unroll") for (int it = 0; it < 4; ++it) ca[buf][it] = *(const LAS bf16x8*)(pCq + 16 * it * RSQ + 64 * (s)); } while (0)
; __device__ __forceinline__ void ret_item(LAS unsigned char* lds, const bf16_t* proj, bf16_t* OD, int b, int h, int dir, int vs, float lg2) {
;     ...
;         {   bf16x8 ca[2][4];
;     ...
;             LDS_C(0, 0);
; #pragma unroll
;             for (int s = 0; s < 8; ++s) { if (s < 7) LDS_C((s + 1) & 1, s + 1); SCHED();
;                 u32x4 bw; bw.x = cvtpk(st[2 * s][0], st[2 * s][1]); bw.y = cvtpk(st[2 * s][2], st[2 * s][3]); bw.z = cvtpk(st[2 * s + 1][0], st[2 * s + 1][1]); bw.w = cvtpk(st[2 * s + 1][2], st[2 * s + 1][3]);
;                 const bf16x8 bs = __builtin_bit_cast(bf16x8, bw);
;                 __builtin_amdgcn_s_setprio(1);
; #pragma unroll
;                 for (int it = 0; it < 4; ++it) acc[it] = MF16(bs, ca[s & 1][it], acc[it]);
;                 __builtin_amdgcn_s_setprio(0); SCHED(); }
	v_mfma_f32_16x16x32_bf16 v[112:115], v[136:139], v[112:115], 0
	s_waitcnt lgkmcnt(3)
	v_mfma_f32_16x16x32_bf16 v[120:123], v[136:139], v[120:123], 0
	s_waitcnt lgkmcnt(1)
	v_mfma_f32_16x16x32_bf16 v[128:131], v[136:139], v[128:131], 0
	s_setprio 0
	ds_read_b128 v[136:139], v231 offset:128
	ds_read_b128 v[140:143], v231 offset:9344
	ds_read_b128 v[144:147], v231 offset:18560
	ds_read_b128 v[148:151], v231 offset:27776
	v_cvt_pk_bf16_f32 v152, v48, v49
	v_cvt_pk_bf16_f32 v153, v50, v51
	v_cvt_pk_bf16_f32 v154, v44, v45
	v_cvt_pk_bf16_f32 v155, v46, v47
	s_setprio 1
	v_mfma_f32_16x16x32_bf16 v[104:107], v[152:155], v[108:111], v[104:107]
	v_mfma_f32_16x16x32_bf16 v[108:111], v[152:155], v[116:119], v[112:115]
	v_mfma_f32_16x16x32_bf16 v[112:115], v[152:155], v[124:127], v[120:123]
	s_waitcnt lgkmcnt(4)
	v_mfma_f32_16x16x32_bf16 v[116:119], v[152:155], v[132:135], v[128:131]
	s_setprio 0
	ds_read_b128 v[120:123], v231 offset:192
	ds_read_b128 v[124:127], v231 offset:9408
	ds_read_b128 v[128:131], v231 offset:18624
	ds_read_b128 v[132:135], v231 offset:27840
	v_cvt_pk_bf16_f32 v152, v68, v69
	v_cvt_pk_bf16_f32 v153, v70, v71
	v_cvt_pk_bf16_f32 v154, v64, v65
	v_cvt_pk_bf16_f32 v155, v66, v67
	s_setprio 1
	s_waitcnt lgkmcnt(7)
	v_mfma_f32_16x16x32_bf16 v[104:107], v[152:155], v[136:139], v[104:107]
	s_waitcnt lgkmcnt(6)
	v_mfma_f32_16x16x32_bf16 v[108:111], v[152:155], v[140:143], v[108:111]
	s_waitcnt lgkmcnt(5)
	v_mfma_f32_16x16x32_bf16 v[112:115], v[152:155], v[144:147], v[112:115]
	s_waitcnt lgkmcnt(4)
	v_mfma_f32_16x16x32_bf16 v[116:119], v[152:155], v[148:151], v[116:119]
	s_setprio 0
	ds_read_b128 v[136:139], v231 offset:256
	ds_read_b128 v[140:143], v231 offset:9472
	ds_read_b128 v[144:147], v231 offset:18688
	ds_read_b128 v[148:151], v231 offset:27904
	v_cvt_pk_bf16_f32 v152, v60, v61
	v_cvt_pk_bf16_f32 v153, v62, v63
	v_cvt_pk_bf16_f32 v154, v56, v57
	v_cvt_pk_bf16_f32 v155, v58, v59
	s_setprio 1
	s_waitcnt lgkmcnt(7)
	v_mfma_f32_16x16x32_bf16 v[104:107], v[152:155], v[120:123], v[104:107]
	s_waitcnt lgkmcnt(6)
	v_mfma_f32_16x16x32_bf16 v[108:111], v[152:155], v[124:127], v[108:111]
	s_waitcnt lgkmcnt(5)
	v_mfma_f32_16x16x32_bf16 v[112:115], v[152:155], v[128:131], v[112:115]
	s_waitcnt lgkmcnt(4)
	v_mfma_f32_16x16x32_bf16 v[116:119], v[152:155], v[132:135], v[116:119]
	s_setprio 0
	ds_read_b128 v[120:123], v231 offset:320
	ds_read_b128 v[124:127], v231 offset:9536
	ds_read_b128 v[128:131], v231 offset:18752
	ds_read_b128 v[132:135], v231 offset:27968
	v_cvt_pk_bf16_f32 v152, v88, v89
	v_cvt_pk_bf16_f32 v153, v90, v91
	v_cvt_pk_bf16_f32 v154, v80, v81
	v_cvt_pk_bf16_f32 v155, v82, v83
	s_setprio 1
	s_waitcnt lgkmcnt(7)
	v_mfma_f32_16x16x32_bf16 v[104:107], v[152:155], v[136:139], v[104:107]
	s_waitcnt lgkmcnt(6)
	v_mfma_f32_16x16x32_bf16 v[108:111], v[152:155], v[140:143], v[108:111]
	s_waitcnt lgkmcnt(5)
	v_mfma_f32_16x16x32_bf16 v[112:115], v[152:155], v[144:147], v[112:115]
	s_waitcnt lgkmcnt(4)
	v_mfma_f32_16x16x32_bf16 v[116:119], v[152:155], v[148:151], v[116:119]
	s_setprio 0
	ds_read_b128 v[136:139], v231 offset:384
	ds_read_b128 v[140:143], v231 offset:9600
	ds_read_b128 v[144:147], v231 offset:18816
	ds_read_b128 v[148:151], v231 offset:28032
	v_cvt_pk_bf16_f32 v152, v76, v77
	v_cvt_pk_bf16_f32 v153, v78, v79
	v_cvt_pk_bf16_f32 v154, v72, v73
	v_cvt_pk_bf16_f32 v155, v74, v75
	s_setprio 1
	s_waitcnt lgkmcnt(7)
	v_mfma_f32_16x16x32_bf16 v[104:107], v[152:155], v[120:123], v[104:107]
	s_waitcnt lgkmcnt(6)
	v_mfma_f32_16x16x32_bf16 v[108:111], v[152:155], v[124:127], v[108:111]
	s_waitcnt lgkmcnt(5)
	v_mfma_f32_16x16x32_bf16 v[112:115], v[152:155], v[128:131], v[112:115]
	s_waitcnt lgkmcnt(4)
	v_mfma_f32_16x16x32_bf16 v[116:119], v[152:155], v[132:135], v[116:119]
	s_setprio 0
	ds_read_b128 v[120:123], v231 offset:448
	ds_read_b128 v[124:127], v231 offset:9664
	ds_read_b128 v[128:131], v231 offset:18880
	ds_read_b128 v[132:135], v231 offset:28096
	v_cvt_pk_bf16_f32 v152, v92, v93
	v_cvt_pk_bf16_f32 v153, v94, v95
	v_cvt_pk_bf16_f32 v154, v84, v85
	v_cvt_pk_bf16_f32 v155, v86, v87
	s_setprio 1
	s_waitcnt lgkmcnt(7)
	v_mfma_f32_16x16x32_bf16 v[104:107], v[152:155], v[136:139], v[104:107]
	s_waitcnt lgkmcnt(6)
	v_mfma_f32_16x16x32_bf16 v[108:111], v[152:155], v[140:143], v[108:111]
	s_waitcnt lgkmcnt(5)
	v_mfma_f32_16x16x32_bf16 v[112:115], v[152:155], v[144:147], v[112:115]
	s_waitcnt lgkmcnt(4)
	v_mfma_f32_16x16x32_bf16 v[116:119], v[152:155], v[148:151], v[116:119]
	s_setprio 0
	v_cvt_pk_bf16_f32 v136, v96, v97
	v_cvt_pk_bf16_f32 v137, v98, v99
	v_cvt_pk_bf16_f32 v138, v100, v101
	v_cvt_pk_bf16_f32 v139, v102, v103
	s_setprio 1
	s_waitcnt lgkmcnt(3)
	v_mfma_f32_16x16x32_bf16 v[104:107], v[136:139], v[120:123], v[104:107]
	s_waitcnt lgkmcnt(2)
	v_mfma_f32_16x16x32_bf16 v[108:111], v[136:139], v[124:127], v[108:111]
	s_waitcnt lgkmcnt(1)
	v_mfma_f32_16x16x32_bf16 v[112:115], v[136:139], v[128:131], v[112:115]
	s_waitcnt lgkmcnt(0)
	v_mfma_f32_16x16x32_bf16 v[116:119], v[136:139], v[132:135], v[116:119]
	s_setprio 0
	s_waitcnt lgkmcnt(0)
	s_barrier
; #define LAS __attribute__((address_space(3)))
; __device__ __forceinline__ unsigned cvtpk(float lo, float hi) { unsigned r; asm volatile("v_cvt_pk_bf16_f32 %0, %1, %2" : "=v"(r) : "v"(lo), "v"(hi)); return r; }
; __device__ __forceinline__ s16x4 trd(LAS unsigned char* p) { return __builtin_bit_cast(s16x4, __builtin_amdgcn_ds_read_tr16_b64_v4i16((LAS s16x4*)p)); }
; __device__ __forceinline__ bf16x8 cat(s16x4 a, s16x4 b) { return (bf16x8){a[0], a[1], a[2], a[3], b[0], b[1], b[2], b[3]}; }
; #define MF16(a, b, c) __builtin_amdgcn_mfma_f32_16x16x32_bf16((a), (b), (c), 0, 0, 0)
; #define SCHED() __builtin_amdgcn_sched_barrier(0)
; __device__ __forceinline__ void ret_item(LAS unsigned char* lds, const bf16_t* proj, bf16_t* OD, int b, int h, int dir, int vs, float lg2) {
;     ...
;         bf16x8 bv[2], ia[2][4];
; #pragma unroll
;         for (int s = 0; s < 2; ++s) { bv[s] = cat(trd(pVt + 32 * s * RSV), trd(pVt + (32 * s + 4) * RSV));
; #pragma unroll
;             for (int it = 0; it < 4; ++it) ia[s][it] = *(const LAS bf16x8*)(pIs + 16 * it * RSS + 64 * s); }
;         s16x4 ua[2][4][2];
;     ...
;         LDS_U(0, 0);
;         SCHED();
; #pragma unroll
;         for (int it = 0; it < 4; ++it) { const int ex = dir ? 3 - it : it; const float cq = qdl * (ex == 0 ? 1.f : ex == 1 ? c16 : ex == 2 ? c32 : c48); acc[it] = acc[it] * cq; }
; #pragma unroll
;         for (int s = 0; s < 2; ++s)
; #pragma unroll
;             for (int it = 0; it < 4; ++it) acc[it] = MF16(bv[s], ia[s][it], acc[it]);
;         SCHED();
; #pragma unroll
;         for (int i = 0; i < 16; ++i) st[i] = st[i] * cd;
;         bf16x8 bvd[2];
; #pragma unroll
;         for (int s = 0; s < 2; ++s) { const float ck = (dir ? s : 1 - s) ? c32 : 1.f; float e[8];
; #pragma unroll
;             for (int jj = 0; jj < 8; ++jj) e[jj] = bf2f((unsigned short)bv[s][jj]) * (kd8[jj] * ck);
;             u32x4 bw; bw.x = cvtpk(e[0], e[1]); bw.y = cvtpk(e[2], e[3]); bw.z = cvtpk(e[4], e[5]); bw.w = cvtpk(e[6], e[7]);
;             bvd[s] = __builtin_bit_cast(bf16x8, bw); }
; #pragma unroll
;         for (int u = 0; u < 8; ++u) { if (u < 7) LDS_U((u + 1) & 1, u + 1); SCHED();
;             __builtin_amdgcn_s_setprio(1);
; #pragma unroll
;             for (int k = 0; k < 4; ++k) st[4 * (u & 3) + k] = MF16(cat(ua[u & 1][k][0], ua[u & 1][k][1]), bvd[u >> 2], st[4 * (u & 3) + k]);
	ds_read_b64_tr_b16 v[140:141], v232
	ds_read_b64_tr_b16 v[142:143], v232 offset:1088
	ds_read_b64_tr_b16 v[136:137], v232 offset:8704
	ds_read_b64_tr_b16 v[138:139], v232 offset:9792
	ds_read_b128 v[144:147], v233
	ds_read_b128 v[148:151], v233 offset:64
	ds_read_b128 v[152:155], v233 offset:2304
	ds_read_b128 v[156:159], v233 offset:2368
	ds_read_b128 v[236:239], v233 offset:4608
	ds_read_b128 v[240:243], v233 offset:4672
	ds_read_b128 v[244:247], v233 offset:6912
	ds_read_b128 v[248:251], v233 offset:6976
	v_add_u32_e32 v235, v204, v203
	ds_read_b64_tr_b16 v[128:129], v235 offset:36864
	ds_read_b64_tr_b16 v[130:131], v235 offset:39168
	ds_read_b64_tr_b16 v[126:127], v235 offset:39232
	ds_read_b64_tr_b16 v[124:125], v235 offset:36928
	ds_read_b64_tr_b16 v[132:133], v234 offset:36896
	ds_read_b64_tr_b16 v[134:135], v234 offset:39200
	ds_read_b64_tr_b16 v[122:123], v234 offset:39264
	ds_read_b64_tr_b16 v[120:121], v234 offset:36960
	v_pk_mul_f32 v[106:107], v[180:181], v[106:107]
	v_pk_mul_f32 v[104:105], v[178:179], v[104:105]
	v_pk_mul_f32 v[114:115], v[188:189], v[114:115]
	v_pk_mul_f32 v[112:113], v[186:187], v[112:113]
	s_waitcnt lgkmcnt(14)
	v_mfma_f32_16x16x32_bf16 v[104:107], v[140:143], v[144:147], v[104:107]
	v_mul_f32_e64 v110, v184, v110
	v_mul_f32_e64 v111, v185, v111
	v_pk_mul_f32 v[108:109], v[182:183], v[108:109]
	s_waitcnt lgkmcnt(11)
	v_mfma_f32_16x16x32_bf16 v[144:147], v[140:143], v[236:239], v[112:115]
	s_nop 2
	v_mul_f32_e64 v114, v192, v118
	v_mul_f32_e64 v115, v193, v119
	v_pk_mul_f32 v[112:113], v[190:191], v[116:117]
	v_mfma_f32_16x16x32_bf16 v[108:111], v[140:143], v[152:155], v[108:111]
	s_waitcnt lgkmcnt(9)
	v_mfma_f32_16x16x32_bf16 v[152:155], v[140:143], v[244:247], v[112:115]
	v_mfma_f32_16x16x32_bf16 v[116:119], v[136:139], v[148:151], v[104:107]
	v_mfma_f32_16x16x32_bf16 v[112:115], v[136:139], v[156:159], v[108:111]
	v_mfma_f32_16x16x32_bf16 v[108:111], v[136:139], v[240:243], v[144:147]
	s_waitcnt lgkmcnt(8)
	v_mfma_f32_16x16x32_bf16 v[104:107], v[136:139], v[248:251], v[152:155]
	v_mov_b32_e32 v165, v164
	s_nop 1
	v_pk_mul_f32 v[154:155], v[164:165], v[46:47]
	v_pk_mul_f32 v[152:153], v[174:175], v[44:45]
	v_pk_mul_f32 v[46:47], v[164:165], v[70:71]
	v_pk_mul_f32 v[44:45], v[174:175], v[68:69]
	v_pk_mul_f32 v[158:159], v[164:165], v[58:59]
	v_pk_mul_f32 v[156:157], v[174:175], v[56:57]
	v_pk_mul_f32 v[70:71], v[164:165], v[82:83]
	v_pk_mul_f32 v[68:69], v[174:175], v[80:81]
	v_pk_mul_f32 v[82:83], v[164:165], v[78:79]
	v_pk_mul_f32 v[80:81], v[174:175], v[76:77]
	v_pk_mul_f32 v[58:59], v[164:165], v[94:95]
	v_pk_mul_f32 v[56:57], v[174:175], v[92:93]
	v_pk_mul_f32 v[78:79], v[164:165], v[86:87]
	v_pk_mul_f32 v[76:77], v[174:175], v[84:85]
	v_lshlrev_b32_e32 v84, 16, v140
	v_and_b32_e32 v85, 0xffff0000, v140
	v_lshlrev_b32_e32 v86, 16, v141
	v_and_b32_e32 v87, 0xffff0000, v141
	v_lshlrev_b32_e32 v92, 16, v142
	v_and_b32_e32 v93, 0xffff0000, v142
	v_lshlrev_b32_e32 v94, 16, v143
	v_and_b32_e32 v95, 0xffff0000, v143
	v_mul_f32_e32 v84, v208, v84
	v_mul_f32_e32 v85, v209, v85
	v_mul_f32_e32 v86, v210, v86
	v_mul_f32_e32 v87, v211, v87
	v_mul_f32_e32 v92, v212, v92
	v_mul_f32_e32 v93, v213, v93
	v_mul_f32_e32 v94, v214, v94
	v_mul_f32_e32 v95, v215, v95
	v_pk_mul_f32 v[146:147], v[164:165], v[50:51]
	v_pk_mul_f32 v[144:145], v[174:175], v[48:49]
	v_pk_mul_f32 v[50:51], v[164:165], v[90:91]
	v_pk_mul_f32 v[48:49], v[174:175], v[88:89]
	v_pk_mul_f32 v[90:91], v[164:165], v[74:75]
	v_pk_mul_f32 v[88:89], v[174:175], v[72:73]
	v_pk_mul_f32 v[74:75], v[164:165], v[98:99]
	v_pk_mul_f32 v[72:73], v[174:175], v[96:97]
	v_cvt_pk_bf16_f32 v84, v84, v85
	v_cvt_pk_bf16_f32 v85, v86, v87
	v_cvt_pk_bf16_f32 v86, v92, v93
	v_cvt_pk_bf16_f32 v87, v94, v95
	v_lshlrev_b32_e32 v92, 16, v136
	v_and_b32_e32 v93, 0xffff0000, v136
	v_lshlrev_b32_e32 v94, 16, v137
	v_and_b32_e32 v95, 0xffff0000, v137
	v_lshlrev_b32_e32 v96, 16, v138
	v_and_b32_e32 v97, 0xffff0000, v138
	v_lshlrev_b32_e32 v98, 16, v139
	v_and_b32_e32 v99, 0xffff0000, v139
	v_mul_f32_e32 v92, v216, v92
	v_mul_f32_e32 v93, v217, v93
	v_mul_f32_e32 v94, v218, v94
	v_mul_f32_e32 v95, v219, v95
	v_mul_f32_e32 v96, v220, v96
	v_mul_f32_e32 v97, v221, v97
	v_mul_f32_e32 v98, v222, v98
	v_mul_f32_e32 v99, v223, v99
	v_pk_mul_f32 v[150:151], v[164:165], v[62:63]
	v_pk_mul_f32 v[148:149], v[174:175], v[60:61]
	v_pk_mul_f32 v[62:63], v[164:165], v[102:103]
	v_pk_mul_f32 v[60:61], v[174:175], v[100:101]
	v_cvt_pk_bf16_f32 v100, v92, v93
	v_cvt_pk_bf16_f32 v101, v94, v95
	v_cvt_pk_bf16_f32 v102, v96, v97
	v_cvt_pk_bf16_f32 v103, v98, v99
	ds_read_b64_tr_b16 v[92:93], v235 offset:36992
	ds_read_b64_tr_b16 v[94:95], v235 offset:39296
	ds_read_b64_tr_b16 v[96:97], v234 offset:37024
	ds_read_b64_tr_b16 v[98:99], v234 offset:39328
	ds_read_b64_tr_b16 v[136:137], v235 offset:37056
	ds_read_b64_tr_b16 v[138:139], v235 offset:39360
	ds_read_b64_tr_b16 v[140:141], v234 offset:37088
	ds_read_b64_tr_b16 v[142:143], v234 offset:39392
	v_pk_mul_f32 v[42:43], v[164:165], v[42:43]
	v_pk_mul_f32 v[40:41], v[174:175], v[40:41]
	v_pk_mul_f32 v[54:55], v[164:165], v[54:55]
	v_pk_mul_f32 v[52:53], v[174:175], v[52:53]
	v_pk_mul_f32 v[66:67], v[164:165], v[66:67]
	v_pk_mul_f32 v[64:65], v[174:175], v[64:65]
	s_setprio 1
	s_waitcnt lgkmcnt(14)
	v_mfma_f32_16x16x32_bf16 v[40:43], v[128:131], v[84:87], v[40:43]
	s_waitcnt lgkmcnt(10)
	v_mfma_f32_16x16x32_bf16 v[52:55], v[132:135], v[84:87], v[52:55]
	v_mfma_f32_16x16x32_bf16 v[124:127], v[124:127], v[84:87], v[144:147]
	s_waitcnt lgkmcnt(8)
; __device__ __forceinline__ unsigned cvtpk(float lo, float hi) { unsigned r; asm volatile("v_cvt_pk_bf16_f32 %0, %1, %2" : "=v"(r) : "v"(lo), "v"(hi)); return r; }
; __device__ __forceinline__ bf16x8 cat(s16x4 a, s16x4 b) { return (bf16x8){a[0], a[1], a[2], a[3], b[0], b[1], b[2], b[3]}; }
; #define MF16(a, b, c) __builtin_amdgcn_mfma_f32_16x16x32_bf16((a), (b), (c), 0, 0, 0)
; #define RBAR() do { asm volatile("s_waitcnt lgkmcnt(0)" ::: "memory"); __builtin_amdgcn_s_barrier(); asm volatile("" ::: "memory"); } while (0)
; __device__ __forceinline__ unsigned cvtpk(float lo, float hi) { unsigned r; asm volatile("v_cvt_pk_bf16_f32 %0, %1, %2" : "=v"(r) : "v"(lo), "v"(hi)); return r; }
; #define SCHED() __builtin_amdgcn_sched_barrier(0)
; #define LDS_U(buf, u) do { _Pragma("unroll") for (int k = 0; k < 4; ++k) { LAS unsigned char* pb = ((k & 1) ? pKo : pKe) + 32 * ((u) >> 2) * RSQ + 32 * (4 * ((u) & 3) + k); ua[buf][k][0] = trd(pb); ua[buf][k][1] = trd(pb + 4 * RSQ); } } while (0)
; __device__ __forceinline__ void ret_item(LAS unsigned char* lds, const bf16_t* proj, bf16_t* OD, int b, int h, int dir, int vs, float lg2) {
;     ...
;         for (int u = 0; u < 8; ++u) { if (u < 7) LDS_U((u + 1) & 1, u + 1); SCHED();
;             __builtin_amdgcn_s_setprio(1);
; #pragma unroll
;             for (int k = 0; k < 4; ++k) st[4 * (u & 3) + k] = MF16(cat(ua[u & 1][k][0], ua[u & 1][k][1]), bvd[u >> 2], st[4 * (u & 3) + k]);
;             __builtin_amdgcn_s_setprio(0); SCHED(); }
;     ...
; #pragma unroll
;         for (int it = 0; it < 4; ++it) { u32x2 w; w.x = cvtpk(acc[it][0], acc[it][1]); w.y = cvtpk(acc[it][2], acc[it][3]); *(u32x2*)(Og + (t0 + 16 * it + l15) * 4096) = w; }
;         RBAR();
	v_mfma_f32_16x16x32_bf16 v[120:123], v[120:123], v[84:87], v[152:155]
	s_setprio 0
	ds_read_b64_tr_b16 v[128:129], v235 offset:37120
	ds_read_b64_tr_b16 v[130:131], v235 offset:39424
	ds_read_b64_tr_b16 v[134:135], v235 offset:39488
	ds_read_b64_tr_b16 v[132:133], v235 offset:37184
	ds_read_b64_tr_b16 v[144:145], v234 offset:37152
	ds_read_b64_tr_b16 v[146:147], v234 offset:39456
	ds_read_b64_tr_b16 v[154:155], v234 offset:39520
	ds_read_b64_tr_b16 v[152:153], v234 offset:37216
	s_setprio 1
	s_waitcnt lgkmcnt(14)
	v_mfma_f32_16x16x32_bf16 v[92:95], v[92:95], v[84:87], v[44:47]
	s_waitcnt lgkmcnt(12)
	v_mfma_f32_16x16x32_bf16 v[64:67], v[96:99], v[84:87], v[64:67]
	s_waitcnt lgkmcnt(10)
	v_mfma_f32_16x16x32_bf16 v[96:99], v[136:139], v[84:87], v[148:151]
	s_waitcnt lgkmcnt(8)
	v_mfma_f32_16x16x32_bf16 v[136:139], v[140:143], v[84:87], v[156:159]
	s_setprio 0
	ds_read_b64_tr_b16 v[44:45], v235 offset:37248
	ds_read_b64_tr_b16 v[46:47], v235 offset:39552
	ds_read_b64_tr_b16 v[142:143], v235 offset:39616
	ds_read_b64_tr_b16 v[140:141], v235 offset:37312
	ds_read_b64_tr_b16 v[148:149], v234 offset:37280
	ds_read_b64_tr_b16 v[150:151], v234 offset:39584
	ds_read_b64_tr_b16 v[158:159], v234 offset:39648
	ds_read_b64_tr_b16 v[156:157], v234 offset:37344
	s_setprio 1
	s_waitcnt lgkmcnt(14)
	v_mfma_f32_16x16x32_bf16 v[128:131], v[128:131], v[84:87], v[48:51]
	s_waitcnt lgkmcnt(10)
	v_mfma_f32_16x16x32_bf16 v[144:147], v[144:147], v[84:87], v[68:71]
	v_mfma_f32_16x16x32_bf16 v[132:135], v[132:135], v[84:87], v[80:83]
	s_waitcnt lgkmcnt(8)
	v_mfma_f32_16x16x32_bf16 v[152:155], v[152:155], v[84:87], v[88:91]
	s_setprio 0
	ds_read_b64_tr_b16 v[48:49], v235 offset:55296
	ds_read_b64_tr_b16 v[50:51], v235 offset:57600
	ds_read_b64_tr_b16 v[70:71], v235 offset:57664
	ds_read_b64_tr_b16 v[68:69], v235 offset:55360
	ds_read_b64_tr_b16 v[80:81], v234 offset:55328
	ds_read_b64_tr_b16 v[82:83], v234 offset:57632
	ds_read_b64_tr_b16 v[90:91], v234 offset:57696
	ds_read_b64_tr_b16 v[88:89], v234 offset:55392
	s_setprio 1
	s_waitcnt lgkmcnt(14)
	v_mfma_f32_16x16x32_bf16 v[236:239], v[44:47], v[84:87], v[56:59]
	s_waitcnt lgkmcnt(10)
	v_mfma_f32_16x16x32_bf16 v[148:151], v[148:151], v[84:87], v[76:79]
	v_mfma_f32_16x16x32_bf16 v[140:143], v[140:143], v[84:87], v[72:75]
	s_waitcnt lgkmcnt(8)
	v_mfma_f32_16x16x32_bf16 v[156:159], v[156:159], v[84:87], v[60:63]
	s_setprio 0
	ds_read_b64_tr_b16 v[56:57], v235 offset:55424
	ds_read_b64_tr_b16 v[58:59], v235 offset:57728
	ds_read_b64_tr_b16 v[62:63], v235 offset:57792
	ds_read_b64_tr_b16 v[60:61], v235 offset:55488
	ds_read_b64_tr_b16 v[72:73], v234 offset:55456
	ds_read_b64_tr_b16 v[74:75], v234 offset:57760
	ds_read_b64_tr_b16 v[78:79], v234 offset:57824
	ds_read_b64_tr_b16 v[76:77], v234 offset:55520
	s_setprio 1
	s_waitcnt lgkmcnt(14)
	v_mfma_f32_16x16x32_bf16 v[40:43], v[48:51], v[100:103], v[40:43]
	s_waitcnt lgkmcnt(10)
	v_mfma_f32_16x16x32_bf16 v[52:55], v[80:83], v[100:103], v[52:55]
	v_mfma_f32_16x16x32_bf16 v[48:51], v[68:71], v[100:103], v[124:127]
	s_waitcnt lgkmcnt(8)
	v_mfma_f32_16x16x32_bf16 v[44:47], v[88:91], v[100:103], v[120:123]
	s_setprio 0
	ds_read_b64_tr_b16 v[80:81], v235 offset:55552
	ds_read_b64_tr_b16 v[82:83], v235 offset:57856
	ds_read_b64_tr_b16 v[86:87], v235 offset:57920
	ds_read_b64_tr_b16 v[84:85], v235 offset:55616
	ds_read_b64_tr_b16 v[120:121], v234 offset:55584
	ds_read_b64_tr_b16 v[122:123], v234 offset:57888
	ds_read_b64_tr_b16 v[126:127], v234 offset:57952
	ds_read_b64_tr_b16 v[124:125], v234 offset:55648
	s_setprio 1
	s_waitcnt lgkmcnt(14)
	v_mfma_f32_16x16x32_bf16 v[68:71], v[56:59], v[100:103], v[92:95]
	s_waitcnt lgkmcnt(10)
	v_mfma_f32_16x16x32_bf16 v[64:67], v[72:75], v[100:103], v[64:67]
	v_mfma_f32_16x16x32_bf16 v[60:63], v[60:63], v[100:103], v[96:99]
	s_waitcnt lgkmcnt(8)
	v_mfma_f32_16x16x32_bf16 v[56:59], v[76:79], v[100:103], v[136:139]
	s_setprio 0
	ds_read_b64_tr_b16 v[92:93], v235 offset:55680
	ds_read_b64_tr_b16 v[94:95], v235 offset:57984
	ds_read_b64_tr_b16 v[98:99], v235 offset:58048
	ds_read_b64_tr_b16 v[96:97], v235 offset:55744
	ds_read_b64_tr_b16 v[136:137], v234 offset:55712
	ds_read_b64_tr_b16 v[138:139], v234 offset:58016
	ds_read_b64_tr_b16 v[242:243], v234 offset:58080
	ds_read_b64_tr_b16 v[240:241], v234 offset:55776
	s_setprio 1
	s_waitcnt lgkmcnt(14)
	v_mfma_f32_16x16x32_bf16 v[88:91], v[80:83], v[100:103], v[128:131]
	s_waitcnt lgkmcnt(10)
	v_mfma_f32_16x16x32_bf16 v[80:83], v[120:123], v[100:103], v[144:147]
	v_mfma_f32_16x16x32_bf16 v[76:79], v[84:87], v[100:103], v[132:135]
	s_waitcnt lgkmcnt(8)
	v_mfma_f32_16x16x32_bf16 v[72:75], v[124:127], v[100:103], v[152:155]
	s_setprio 0
	s_setprio 1
	s_waitcnt lgkmcnt(6)
	v_mfma_f32_16x16x32_bf16 v[92:95], v[92:95], v[100:103], v[236:239]
	s_waitcnt lgkmcnt(2)
	v_mfma_f32_16x16x32_bf16 v[84:87], v[136:139], v[100:103], v[148:151]
	v_mfma_f32_16x16x32_bf16 v[96:99], v[96:99], v[100:103], v[140:143]
	s_waitcnt lgkmcnt(0)
	v_mfma_f32_16x16x32_bf16 v[100:103], v[240:243], v[100:103], v[156:159]
	s_setprio 0
	v_lshl_or_b32 v176, v176, 18, v224
	v_cvt_pk_bf16_f32 v116, v116, v117
	v_cvt_pk_bf16_f32 v117, v118, v119
	v_lshl_add_u64 v[118:119], v[176:177], 1, v[160:161]
	global_store_dwordx2 v[118:119], v[116:117], off
	v_cvt_pk_bf16_f32 v112, v112, v113
	v_cvt_pk_bf16_f32 v113, v114, v115
	v_ashrrev_i32_e32 v115, 31, v176
	v_mov_b32_e32 v114, v176
	v_lshl_add_u64 v[114:115], v[114:115], 1, v[160:161]
	s_mov_b32 s20, 0x20000
	v_add_co_u32_e32 v116, vcc, s20, v114
	s_mov_b32 s20, 0x40000
	s_nop 0
	v_addc_co_u32_e32 v117, vcc, 0, v115, vcc
	global_store_dwordx2 v[116:117], v[112:113], off
	v_cvt_pk_bf16_f32 v108, v108, v109
	v_cvt_pk_bf16_f32 v109, v110, v111
	v_add_co_u32_e32 v110, vcc, s20, v114
	s_add_i32 s19, s19, -1
	s_nop 0
	v_addc_co_u32_e32 v111, vcc, 0, v115, vcc
	global_store_dwordx2 v[110:111], v[108:109], off
	v_cvt_pk_bf16_f32 v104, v104, v105
	v_cvt_pk_bf16_f32 v105, v106, v107
	v_add_co_u32_e32 v106, vcc, s65, v114
	s_add_i32 s16, s16, 1
	s_nop 0
	v_addc_co_u32_e32 v107, vcc, 0, v115, vcc
	global_store_dwordx2 v[106:107], v[104:105], off
	s_waitcnt lgkmcnt(0)
	s_barrier
	s_cmp_lg_u32 s19, -2
	s_cbranch_scc0 .LBB0_138
